# prologue weight transposes: worker order reversed so the workgroups with two adaLN GEMV tasks take one transposes item instead of two
# baseline (speedup 1.0000x reference)
; __device__ __forceinline__ void run_transposes(const P& p, unsigned char* lds, int wave, int lane, unsigned mask, int wid, int nw) {
;     float* scr = (float*)(lds + wave * 8448);
;     int base = 0;
; #pragma unroll 1
;     for (int mat = 0; mat < 12; ++mat) {
;         if (!((mask >> mat) & 1u)) continue;
;         const int n = mat_items(mat);
;         int first = (wid - base % nw + nw) % nw;
; #pragma unroll 1
;         for (int it = first; it < n; it += nw) mat_item(p, scr, mat, it, lane);
;         base += n;
.LBB0_8:
	s_cmp_lg_u32 s61, 0
	s_cbranch_scc1 .LBB0_7
	s_abs_i32 s9, s12
	v_readlane_b32 s64, v253, 4
	s_mul_hi_u32 s62, s9, s64
	v_readlane_b32 s63, v253, 3
	s_mul_i32 s62, s62, s63
	s_sub_i32 s9, s9, s62
	s_ashr_i32 s8, s12, 31
	s_sub_i32 s62, s9, s63
	s_cmp_ge_u32 s9, s63
	s_cselect_b32 s9, s62, s9
	s_sub_i32 s62, s9, s63
	s_cmp_ge_u32 s9, s63
	s_cselect_b32 s9, s62, s9
	s_xor_b32 s9, s9, s8
	s_sub_i32 s8, s8, s9
	s_add_i32 s8, s13, s8
	s_ashr_i32 s9, s8, 31
	s_abs_i32 s8, s8
	s_mul_hi_u32 s62, s8, s64
	s_mul_i32 s62, s62, s63
	s_sub_i32 s8, s8, s62
	s_sub_i32 s62, s8, s63
	s_cmp_ge_u32 s8, s63
	s_cselect_b32 s8, s62, s8
	s_sub_i32 s62, s8, s63
	s_cmp_ge_u32 s8, s63
	s_cselect_b32 s8, s62, s8
	s_xor_b32 s8, s8, s9
	s_sub_i32 s62, s8, s9
	s_sub_i32 s62, s4, s62
	s_add_i32 s62, s62, -1
	s_cmpk_gt_i32 s62, 0xaff
	s_cbranch_scc1 .LBB0_6
	s_lshl_b32 s63, s62, 5
	s_lshl_b32 s64, s62, 4

; __device__ __forceinline__ float siluf(float v) { return v * __builtin_amdgcn_rcpf(1.f + __expf(-v)); }
; __device__ __forceinline__ void ph_prologue(const P& p, unsigned char* lds, int tid, int wave, int lane, int G) {
;     ...
;     float* sv = (float*)lds;
;     float* red = (float*)(lds + 36864);
;     bool have = false;
;     typedef float f32x2_ __attribute__((ext_vector_type(2)));
;     for (int task = blockIdx.x; task < 256; task += G) {
;         if (!have) {
;             for (int i = tid; i < 9 * 1024; i += NTHREADS) { const float v = i < 8192 ? p.c[i] : p.c_ctx[i - 8192]; sv[i] = siluf(v); }
;             have = true; __syncthreads();
;         }
;         const int l = task >> 7, c0 = (task & 127) * 72;
;         const bool actv = lane < 36;
;         const float* w = p.ada_w + (size_t)l * DM * 9216 + c0 + 2 * (actv ? lane : 0);
;         float acc0[9], acc1[9];
; #pragma unroll
;         for (int r = 0; r < 9; ++r) { acc0[r] = 0.f; acc1[r] = 0.f; }
;         const int kb = wave * 128;
; #pragma unroll 2
;         for (int k4 = 0; k4 < 128; k4 += 4) {
.LBB0_12:
	s_cmpk_lt_i32 s90, 0x100
	s_cselect_b64 s[8:9], -1, 0
	v_writelane_b32 v253, s8, 5
	s_cmpk_gt_i32 s90, 0xff
	s_nop 0
	v_writelane_b32 v253, s9, 6
	s_barrier
	s_cbranch_scc1 .LBB0_27
	s_lshl_b32 s12, s5, 9
	s_lshl_b32 s24, s5, 7
	s_add_i32 s33, s12, 0
	v_lshlrev_b32_e32 v2, 1, v1
	v_cmp_gt_u32_e64 s[8:9], 36, v1
	s_add_u32 s34, s22, 0x100000
	v_ashrrev_i32_e32 v147, 31, v146
	v_cndmask_b32_e64 v4, 0, v2, s[8:9]
	s_addc_u32 s35, s23, 0
	v_lshl_add_u64 v[2:3], v[146:147], 2, s[20:21]
	s_mul_i32 s20, s5, 0x480000
	s_mul_hi_i32 s21, s24, 0x9000
	s_add_u32 s18, s18, s20
	v_lshlrev_b32_e32 v4, 2, v4
	v_mov_b32_e32 v5, 0
	s_addc_u32 s19, s19, s21
	v_lshl_add_u64 v[6:7], s[18:19], 0, v[4:5]
	s_mov_b64 s[18:19], 0x3f000
	s_movk_i32 s10, 0x2400
	s_movk_i32 s12, 0x288
	v_lshl_add_u32 v8, v1, 3, 0
	s_mul_i32 s26, s5, 0xa20
	v_lshl_add_u64 v[6:7], v[6:7], 0, s[18:19]
	s_movk_i32 s18, 0x8000
	v_cmp_gt_i32_e64 s[10:11], s10, v146
	v_cmp_gt_i32_e64 s[12:13], s12, v146
	v_lshl_add_u32 v1, v146, 2, 0
	s_mov_b32 s5, 0x9000
	s_mov_b64 s[24:25], 0
	s_movk_i32 s40, 0x2000
	s_mov_b32 s19, -1
	s_mov_b64 s[20:21], 0x800
	s_movk_i32 s41, 0x21ff
	s_mov_b32 s42, 0xfffc1000
	s_mov_b32 s43, 0xfffca000
	s_mov_b32 s44, 0xfffd3000
	s_mov_b32 s45, 0xfffdc000
	s_mov_b32 s46, 0xfffe5000
	s_mov_b32 s47, 0xfffee000
	s_mov_b32 s48, 0xffff7000
	s_mov_b64 s[22:23], 0x48000
	v_add_u32_e32 v36, s26, v8
	s_add_i32 s49, 0, 0x9000
	s_mov_b32 s50, 0x38e38e39
	s_movk_i32 s51, 0xffb8
	s_movk_i32 s52, 0x87
	s_mov_b32 s53, s90
	s_mov_b32 s54, s90
	s_branch .LBB0_15
	s_nop 0
	s_nop 0
	s_nop 0
	s_nop 0
	s_nop 0
	s_nop 0
	s_nop 0
	s_nop 0
	s_nop 0
	s_nop 0
	s_nop 0
	s_nop 0
	s_nop 0
	s_nop 0
